# v104: static raise for waves 0-3 applied per tile for the main loop only (priority reset at the start of every tile epilogue)
# baseline (speedup 1.0000x reference)
.LBB0_387:
	v_readlane_b32 vcc_lo, v254, 63
	s_cmp_lt_u32 vcc_lo, 4
	s_cbranch_scc0 .Lprio_done
	s_setprio 1

.LBB0_397:
	s_setprio 0
	v_mov_b32_e32 v179, v235
	v_mov_b32_e32 v239, v236
	s_lshl_b32 s81, s17, 8
	v_add_u32_e32 v0, s67, v179
	v_add_u32_e32 v186, s81, v0
	s_cmp_lt_i32 s47, 5
	s_mov_b64 s[2:3], -1
	s_cbranch_scc1 .LBB0_407
	s_cmp_lt_i32 s47, 6
	s_cbranch_scc1 .LBB0_404
	s_cmp_gt_i32 s47, 6
	s_cbranch_scc0 .LBB0_401
	s_lshl_b32 s2, s48, 8
	s_or_b32 s2, s2, s68
	v_lshl_add_u32 v218, v239, 3, s2
	v_lshl_add_u32 v138, s12, 8, v0
	v_readlane_b32 s14, v255, 20
	v_readlane_b32 s15, v255, 21
	s_lshl_b32 s3, s48, 7
	v_add_u32_e32 v174, 0, v138
	v_and_b32_e32 v174, 0x7f, v174
	v_or_b32_e32 v174, s3, v174
	v_lshlrev_b32_e32 v174, 2, v174
	global_load_dword v170, v174, s[14:15]
	v_add_u32_e32 v174, 16, v138
	v_and_b32_e32 v174, 0x7f, v174
	v_or_b32_e32 v174, s3, v174
	v_lshlrev_b32_e32 v174, 2, v174
	global_load_dword v171, v174, s[14:15]
	v_add_u32_e32 v174, 32, v138
	v_and_b32_e32 v174, 0x7f, v174
	v_or_b32_e32 v174, s3, v174
	v_lshlrev_b32_e32 v174, 2, v174
	global_load_dword v172, v174, s[14:15]
	v_add_u32_e32 v174, 48, v138
	v_and_b32_e32 v174, 0x7f, v174
	v_or_b32_e32 v174, s3, v174
	v_lshlrev_b32_e32 v174, 2, v174
	global_load_dword v173, v174, s[14:15]
	v_ashrrev_i32_e32 v219, 31, v218
	v_lshlrev_b64 v[196:197], 1, v[218:219]
	v_ashrrev_i32_e32 v139, 31, v138
	v_add_u32_e32 v206, 16, v138
	v_lshl_add_u64 v[140:141], s[76:77], 0, v[196:197]
	v_lshlrev_b64 v[204:205], 11, v[138:139]
	v_ashrrev_i32_e32 v207, 31, v206
	v_add_u32_e32 v208, 32, v138
	v_lshl_add_u64 v[220:221], v[218:219], 2, s[36:37]
	v_lshl_add_u64 v[142:143], v[140:141], 0, v[204:205]
	v_lshlrev_b64 v[202:203], 11, v[206:207]
	v_ashrrev_i32_e32 v209, 31, v208
	v_add_u32_e32 v210, 48, v138
	global_load_dwordx4 v[130:133], v[220:221], off offset:16
	global_load_dwordx4 v[134:137], v[220:221], off
	global_load_dwordx4 v[240:243], v[142:143], off
	v_lshl_add_u64 v[142:143], v[140:141], 0, v[202:203]
	v_lshlrev_b64 v[200:201], 11, v[208:209]
	v_ashrrev_i32_e32 v211, 31, v210
	global_load_dwordx4 v[162:165], v[142:143], off
	v_lshl_add_u64 v[142:143], v[140:141], 0, v[200:201]
	v_lshlrev_b64 v[198:199], 11, v[210:211]
	s_mov_b64 s[2:3], 0x40000
	v_add_u32_e32 v212, 0x90, v138
	global_load_dwordx4 v[158:161], v[142:143], off
	v_lshl_add_u64 v[142:143], v[140:141], 0, v[198:199]
	v_lshl_add_u64 v[194:195], v[204:205], 0, s[2:3]
	v_ashrrev_i32_e32 v213, 31, v212
	v_add_u32_e32 v214, 0xa0, v138
	v_add_u32_e32 v216, 0xb0, v138
	v_readlane_b32 s8, v255, 9
	global_load_dwordx4 v[154:157], v[142:143], off
	v_lshl_add_u64 v[142:143], v[140:141], 0, v[194:195]
	v_lshlrev_b64 v[192:193], 11, v[212:213]
	v_ashrrev_i32_e32 v215, 31, v214
	v_ashrrev_i32_e32 v217, 31, v216
	v_readlane_b32 s9, v255, 10
	s_lshl_b32 s2, s48, 7
	v_and_b32_e32 v0, 0x7f, v0
	global_load_dwordx4 v[150:153], v[142:143], off
	v_lshl_add_u64 v[142:143], v[140:141], 0, v[192:193]
	v_lshlrev_b64 v[190:191], 11, v[214:215]
	v_lshlrev_b64 v[188:189], 11, v[216:217]
	v_lshl_add_u64 v[222:223], s[8:9], 0, v[196:197]
	v_or_b32_e32 v196, s2, v0
	v_readlane_b32 s10, v255, 20
	global_load_dwordx4 v[146:149], v[142:143], off
	v_lshl_add_u64 v[142:143], v[140:141], 0, v[190:191]
	v_lshl_add_u64 v[138:139], v[140:141], 0, v[188:189]
	v_ashrrev_i32_e32 v197, 31, v196
	v_readlane_b32 s11, v255, 21
	global_load_dwordx4 v[142:145], v[142:143], off
	s_waitcnt vmcnt(0)
	v_lshlrev_b32_e32 v252, 16, v240
	global_load_dwordx4 v[138:141], v[138:139], off
	v_lshl_add_u64 v[196:197], v[196:197], 2, s[10:11]
	global_load_dword v0, v[196:197], off
	v_and_b32_e32 v253, 0xffff0000, v240
	s_waitcnt vmcnt(0)
	v_pk_fma_f32 v[246:247], v[126:127], v[134:135], v[0:1] op_sel_hi:[1,1,0]
	s_nop 0
	v_pk_mul_f32 v[246:247], v[246:247], v[252:253]
	v_pk_fma_f32 v[244:245], v[128:129], v[136:137], v[0:1] op_sel_hi:[1,1,0]
	v_cvt_pk_bf16_f32 v240, v246, v247
	v_lshlrev_b32_e32 v246, 16, v241
	v_and_b32_e32 v247, 0xffff0000, v241
	v_pk_mul_f32 v[244:245], v[244:245], v[246:247]
	v_pk_fma_f32 v[250:251], v[122:123], v[130:131], v[0:1] op_sel_hi:[1,1,0]
	v_cvt_pk_bf16_f32 v241, v244, v245
	v_lshlrev_b32_e32 v244, 16, v242
	v_and_b32_e32 v245, 0xffff0000, v242
	v_pk_mul_f32 v[244:245], v[250:251], v[244:245]
	v_pk_fma_f32 v[248:249], v[124:125], v[132:133], v[0:1] op_sel_hi:[1,1,0]
	v_cvt_pk_bf16_f32 v242, v244, v245
	v_lshlrev_b32_e32 v244, 16, v243
	v_and_b32_e32 v245, 0xffff0000, v243
	v_and_b32_e32 v0, 0x7f, v206
	v_pk_mul_f32 v[244:245], v[248:249], v[244:245]
	v_or_b32_e32 v206, s2, v0
	v_cvt_pk_bf16_f32 v243, v244, v245
	v_lshl_add_u64 v[244:245], v[222:223], 0, v[204:205]
	v_ashrrev_i32_e32 v207, 31, v206
	global_store_dwordx4 v[244:245], v[240:243], off
	v_lshl_add_u64 v[206:207], v[206:207], 2, s[10:11]
	v_mov_b32_e32 v0, v171
	v_lshlrev_b32_e32 v248, 16, v162
	v_and_b32_e32 v249, 0xffff0000, v162
	v_pk_fma_f32 v[242:243], v[110:111], v[134:135], v[0:1] op_sel_hi:[1,1,0]
	s_nop 0
	v_pk_mul_f32 v[242:243], v[242:243], v[248:249]
	v_pk_fma_f32 v[240:241], v[112:113], v[136:137], v[0:1] op_sel_hi:[1,1,0]
	v_cvt_pk_bf16_f32 v162, v242, v243
	v_lshlrev_b32_e32 v242, 16, v163
	v_and_b32_e32 v243, 0xffff0000, v163
	v_pk_mul_f32 v[240:241], v[240:241], v[242:243]
	v_pk_fma_f32 v[246:247], v[106:107], v[130:131], v[0:1] op_sel_hi:[1,1,0]
	v_cvt_pk_bf16_f32 v163, v240, v241
	v_lshlrev_b32_e32 v240, 16, v164
	v_and_b32_e32 v241, 0xffff0000, v164
	v_pk_mul_f32 v[240:241], v[246:247], v[240:241]
	v_pk_fma_f32 v[244:245], v[108:109], v[132:133], v[0:1] op_sel_hi:[1,1,0]
	v_cvt_pk_bf16_f32 v164, v240, v241
	v_lshlrev_b32_e32 v240, 16, v165
	v_and_b32_e32 v241, 0xffff0000, v165
	v_pk_mul_f32 v[240:241], v[244:245], v[240:241]
	v_and_b32_e32 v0, 0x7f, v208
	v_cvt_pk_bf16_f32 v165, v240, v241
	v_lshl_add_u64 v[240:241], v[222:223], 0, v[202:203]
	global_store_dwordx4 v[240:241], v[162:165], off
	v_lshlrev_b32_e32 v244, 16, v158
	v_and_b32_e32 v245, 0xffff0000, v158
	v_or_b32_e32 v162, s2, v0
	v_ashrrev_i32_e32 v163, 31, v162
	v_lshl_add_u64 v[208:209], v[162:163], 2, s[10:11]
	v_mov_b32_e32 v0, v172
	v_pk_fma_f32 v[164:165], v[94:95], v[134:135], v[0:1] op_sel_hi:[1,1,0]
	s_nop 0
	v_pk_mul_f32 v[164:165], v[164:165], v[244:245]
	v_pk_fma_f32 v[162:163], v[96:97], v[136:137], v[0:1] op_sel_hi:[1,1,0]
	v_cvt_pk_bf16_f32 v158, v164, v165
	v_lshlrev_b32_e32 v164, 16, v159
	v_and_b32_e32 v165, 0xffff0000, v159
	v_pk_mul_f32 v[162:163], v[162:163], v[164:165]
	v_pk_fma_f32 v[242:243], v[90:91], v[130:131], v[0:1] op_sel_hi:[1,1,0]
	v_cvt_pk_bf16_f32 v159, v162, v163
	v_lshlrev_b32_e32 v162, 16, v160
	v_and_b32_e32 v163, 0xffff0000, v160
	v_pk_mul_f32 v[162:163], v[242:243], v[162:163]
	v_pk_fma_f32 v[240:241], v[92:93], v[132:133], v[0:1] op_sel_hi:[1,1,0]
	v_cvt_pk_bf16_f32 v160, v162, v163
	v_lshlrev_b32_e32 v162, 16, v161
	v_and_b32_e32 v163, 0xffff0000, v161
	v_pk_mul_f32 v[162:163], v[240:241], v[162:163]
	v_and_b32_e32 v0, 0x7f, v210
	v_cvt_pk_bf16_f32 v161, v162, v163
	v_lshl_add_u64 v[162:163], v[222:223], 0, v[200:201]
	global_store_dwordx4 v[162:163], v[158:161], off
	v_lshlrev_b32_e32 v240, 16, v154
	v_and_b32_e32 v241, 0xffff0000, v154
	v_or_b32_e32 v158, s2, v0
	v_ashrrev_i32_e32 v159, 31, v158
	v_lshl_add_u64 v[210:211], v[158:159], 2, s[10:11]
	v_mov_b32_e32 v0, v173
	v_pk_fma_f32 v[160:161], v[78:79], v[134:135], v[0:1] op_sel_hi:[1,1,0]
	s_nop 0
	v_pk_mul_f32 v[160:161], v[160:161], v[240:241]
	v_pk_fma_f32 v[158:159], v[80:81], v[136:137], v[0:1] op_sel_hi:[1,1,0]
	v_cvt_pk_bf16_f32 v154, v160, v161
	v_lshlrev_b32_e32 v160, 16, v155
	v_and_b32_e32 v161, 0xffff0000, v155
	v_pk_mul_f32 v[158:159], v[158:159], v[160:161]
	v_pk_fma_f32 v[164:165], v[74:75], v[130:131], v[0:1] op_sel_hi:[1,1,0]
	v_cvt_pk_bf16_f32 v155, v158, v159
	v_lshlrev_b32_e32 v158, 16, v156
	v_and_b32_e32 v159, 0xffff0000, v156
	v_pk_mul_f32 v[158:159], v[164:165], v[158:159]
	v_pk_fma_f32 v[162:163], v[76:77], v[132:133], v[0:1] op_sel_hi:[1,1,0]
	v_cvt_pk_bf16_f32 v156, v158, v159
	v_lshlrev_b32_e32 v158, 16, v157
	v_and_b32_e32 v159, 0xffff0000, v157
	v_pk_mul_f32 v[158:159], v[162:163], v[158:159]
	v_lshlrev_b32_e32 v162, 16, v150
	v_cvt_pk_bf16_f32 v157, v158, v159
	v_lshl_add_u64 v[158:159], v[222:223], 0, v[198:199]
	global_store_dwordx4 v[158:159], v[154:157], off
	v_mov_b32_e32 v0, v170
	v_and_b32_e32 v163, 0xffff0000, v150
	v_pk_fma_f32 v[156:157], v[62:63], v[134:135], v[0:1] op_sel_hi:[1,1,0]
	s_nop 0
	v_pk_mul_f32 v[156:157], v[156:157], v[162:163]
	v_pk_fma_f32 v[154:155], v[64:65], v[136:137], v[0:1] op_sel_hi:[1,1,0]
	v_cvt_pk_bf16_f32 v150, v156, v157
	v_lshlrev_b32_e32 v156, 16, v151
	v_and_b32_e32 v157, 0xffff0000, v151
	v_pk_mul_f32 v[154:155], v[154:155], v[156:157]
	v_pk_fma_f32 v[160:161], v[58:59], v[130:131], v[0:1] op_sel_hi:[1,1,0]
	v_cvt_pk_bf16_f32 v151, v154, v155
	v_lshlrev_b32_e32 v154, 16, v152
	v_and_b32_e32 v155, 0xffff0000, v152
	v_pk_mul_f32 v[154:155], v[160:161], v[154:155]
	v_pk_fma_f32 v[158:159], v[60:61], v[132:133], v[0:1] op_sel_hi:[1,1,0]
	v_cvt_pk_bf16_f32 v152, v154, v155
	v_lshlrev_b32_e32 v154, 16, v153
	v_and_b32_e32 v155, 0xffff0000, v153
	v_pk_mul_f32 v[154:155], v[158:159], v[154:155]
	v_and_b32_e32 v0, 0x7f, v212
	v_cvt_pk_bf16_f32 v153, v154, v155
	v_lshl_add_u64 v[154:155], v[222:223], 0, v[194:195]
	global_store_dwordx4 v[154:155], v[150:153], off
	v_lshlrev_b32_e32 v158, 16, v146
	v_and_b32_e32 v159, 0xffff0000, v146
	v_or_b32_e32 v150, s2, v0
	v_ashrrev_i32_e32 v151, 31, v150
	v_lshl_add_u64 v[212:213], v[150:151], 2, s[10:11]
	v_mov_b32_e32 v0, v171
	v_pk_fma_f32 v[152:153], v[46:47], v[134:135], v[0:1] op_sel_hi:[1,1,0]
	s_nop 0
	v_pk_mul_f32 v[152:153], v[152:153], v[158:159]
	v_pk_fma_f32 v[150:151], v[48:49], v[136:137], v[0:1] op_sel_hi:[1,1,0]
	v_cvt_pk_bf16_f32 v146, v152, v153
	v_lshlrev_b32_e32 v152, 16, v147
	v_and_b32_e32 v153, 0xffff0000, v147
	v_pk_mul_f32 v[150:151], v[150:151], v[152:153]
	v_pk_fma_f32 v[156:157], v[42:43], v[130:131], v[0:1] op_sel_hi:[1,1,0]
	v_cvt_pk_bf16_f32 v147, v150, v151
	v_lshlrev_b32_e32 v150, 16, v148
	v_and_b32_e32 v151, 0xffff0000, v148
	v_pk_mul_f32 v[150:151], v[156:157], v[150:151]
	v_pk_fma_f32 v[154:155], v[44:45], v[132:133], v[0:1] op_sel_hi:[1,1,0]
	v_cvt_pk_bf16_f32 v148, v150, v151
	v_lshlrev_b32_e32 v150, 16, v149
	v_and_b32_e32 v151, 0xffff0000, v149
	v_pk_mul_f32 v[150:151], v[154:155], v[150:151]
	v_and_b32_e32 v0, 0x7f, v214
	v_cvt_pk_bf16_f32 v149, v150, v151
	v_lshl_add_u64 v[150:151], v[222:223], 0, v[192:193]
	global_store_dwordx4 v[150:151], v[146:149], off
	v_lshlrev_b32_e32 v154, 16, v142
	v_and_b32_e32 v155, 0xffff0000, v142
	v_or_b32_e32 v146, s2, v0
	v_ashrrev_i32_e32 v147, 31, v146
	v_lshl_add_u64 v[214:215], v[146:147], 2, s[10:11]
	v_mov_b32_e32 v0, v172
	v_pk_fma_f32 v[148:149], v[30:31], v[134:135], v[0:1] op_sel_hi:[1,1,0]
	s_nop 0
	v_pk_mul_f32 v[148:149], v[148:149], v[154:155]
	v_pk_fma_f32 v[146:147], v[32:33], v[136:137], v[0:1] op_sel_hi:[1,1,0]
	v_cvt_pk_bf16_f32 v142, v148, v149
	v_lshlrev_b32_e32 v148, 16, v143
	v_and_b32_e32 v149, 0xffff0000, v143
	v_pk_mul_f32 v[146:147], v[146:147], v[148:149]
	v_pk_fma_f32 v[152:153], v[26:27], v[130:131], v[0:1] op_sel_hi:[1,1,0]
	v_cvt_pk_bf16_f32 v143, v146, v147
	v_lshlrev_b32_e32 v146, 16, v144
	v_and_b32_e32 v147, 0xffff0000, v144
	v_pk_mul_f32 v[146:147], v[152:153], v[146:147]
	v_pk_fma_f32 v[150:151], v[28:29], v[132:133], v[0:1] op_sel_hi:[1,1,0]
	v_cvt_pk_bf16_f32 v144, v146, v147
	v_lshlrev_b32_e32 v146, 16, v145
	v_and_b32_e32 v147, 0xffff0000, v145
	v_pk_mul_f32 v[146:147], v[150:151], v[146:147]
	v_and_b32_e32 v0, 0x7f, v216
	v_cvt_pk_bf16_f32 v145, v146, v147
	v_lshl_add_u64 v[146:147], v[222:223], 0, v[190:191]
	global_store_dwordx4 v[146:147], v[142:145], off
	s_nop 1
	v_or_b32_e32 v142, s2, v0
	v_ashrrev_i32_e32 v143, 31, v142
	v_lshl_add_u64 v[216:217], v[142:143], 2, s[10:11]
	v_mov_b32_e32 v0, v173
	s_mov_b64 s[2:3], 0
	v_pk_fma_f32 v[134:135], v[14:15], v[134:135], v[0:1] op_sel_hi:[1,1,0]
	v_pk_fma_f32 v[142:143], v[12:13], v[132:133], v[0:1] op_sel_hi:[1,1,0]
	v_pk_fma_f32 v[132:133], v[10:11], v[130:131], v[0:1] op_sel_hi:[1,1,0]
	v_lshlrev_b32_e32 v130, 16, v138
	v_and_b32_e32 v131, 0xffff0000, v138
	v_pk_fma_f32 v[136:137], v[16:17], v[136:137], v[0:1] op_sel_hi:[1,1,0]
	v_pk_mul_f32 v[130:131], v[134:135], v[130:131]
	v_lshlrev_b32_e32 v134, 16, v139
	v_and_b32_e32 v135, 0xffff0000, v139
	v_pk_mul_f32 v[134:135], v[136:137], v[134:135]
	v_cvt_pk_bf16_f32 v130, v130, v131
	v_cvt_pk_bf16_f32 v131, v134, v135
	v_lshlrev_b32_e32 v134, 16, v140
	v_and_b32_e32 v135, 0xffff0000, v140
	v_add_u32_e32 v138, 0x80, v218
	v_pk_mul_f32 v[132:133], v[132:133], v[134:135]
	v_lshlrev_b32_e32 v134, 16, v141
	v_and_b32_e32 v135, 0xffff0000, v141
	v_ashrrev_i32_e32 v139, 31, v138
	v_pk_mul_f32 v[134:135], v[142:143], v[134:135]
	v_lshlrev_b64 v[218:219], 1, v[138:139]
	v_cvt_pk_bf16_f32 v132, v132, v133
	v_cvt_pk_bf16_f32 v133, v134, v135
	v_lshl_add_u64 v[134:135], v[222:223], 0, v[188:189]
	v_lshl_add_u64 v[138:139], s[76:77], 0, v[218:219]
	global_store_dwordx4 v[134:135], v[130:133], off
	v_lshl_add_u64 v[140:141], v[138:139], 0, v[204:205]
	global_load_dwordx4 v[130:133], v[220:221], off offset:528
	global_load_dwordx4 v[134:137], v[220:221], off offset:512
	v_lshl_add_u64 v[218:219], s[8:9], 0, v[218:219]
	global_load_dwordx4 v[220:223], v[140:141], off
	v_lshl_add_u64 v[140:141], v[138:139], 0, v[202:203]
	global_load_dwordx4 v[162:165], v[140:141], off
	v_lshl_add_u64 v[140:141], v[138:139], 0, v[200:201]
	global_load_dwordx4 v[158:161], v[140:141], off
	v_lshl_add_u64 v[140:141], v[138:139], 0, v[198:199]
	global_load_dwordx4 v[154:157], v[140:141], off
	v_lshl_add_u64 v[140:141], v[138:139], 0, v[194:195]
	global_load_dwordx4 v[150:153], v[140:141], off
	v_lshl_add_u64 v[140:141], v[138:139], 0, v[192:193]
	global_load_dwordx4 v[146:149], v[140:141], off
	v_lshl_add_u64 v[140:141], v[138:139], 0, v[190:191]
	v_lshl_add_u64 v[138:139], v[138:139], 0, v[188:189]
	global_load_dwordx4 v[142:145], v[140:141], off
	v_lshl_add_u64 v[204:205], v[218:219], 0, v[204:205]
	global_load_dwordx4 v[138:141], v[138:139], off
	global_load_dword v0, v[196:197], off
	v_lshl_add_u64 v[202:203], v[218:219], 0, v[202:203]
	s_waitcnt vmcnt(8)
	v_lshlrev_b32_e32 v248, 16, v220
	v_and_b32_e32 v249, 0xffff0000, v220
	s_waitcnt vmcnt(0)
	v_pk_fma_f32 v[242:243], v[118:119], v[134:135], v[0:1] op_sel_hi:[1,1,0]
	s_nop 0
	v_pk_mul_f32 v[242:243], v[242:243], v[248:249]
	v_pk_fma_f32 v[240:241], v[120:121], v[136:137], v[0:1] op_sel_hi:[1,1,0]
	v_cvt_pk_bf16_f32 v220, v242, v243
	v_lshlrev_b32_e32 v242, 16, v221
	v_and_b32_e32 v243, 0xffff0000, v221
	v_pk_mul_f32 v[240:241], v[240:241], v[242:243]
	v_pk_fma_f32 v[246:247], v[114:115], v[130:131], v[0:1] op_sel_hi:[1,1,0]
	v_cvt_pk_bf16_f32 v221, v240, v241
	v_lshlrev_b32_e32 v240, 16, v222
	v_and_b32_e32 v241, 0xffff0000, v222
	v_pk_mul_f32 v[240:241], v[246:247], v[240:241]
	v_pk_fma_f32 v[244:245], v[116:117], v[132:133], v[0:1] op_sel_hi:[1,1,0]
	v_cvt_pk_bf16_f32 v222, v240, v241
	v_lshlrev_b32_e32 v240, 16, v223
	v_and_b32_e32 v241, 0xffff0000, v223
	v_pk_mul_f32 v[240:241], v[244:245], v[240:241]
	s_nop 0
	v_cvt_pk_bf16_f32 v223, v240, v241
	global_store_dwordx4 v[204:205], v[220:223], off
	v_mov_b32_e32 v0, v171
	v_lshlrev_b32_e32 v240, 16, v162
	v_and_b32_e32 v241, 0xffff0000, v162
	v_pk_fma_f32 v[206:207], v[102:103], v[134:135], v[0:1] op_sel_hi:[1,1,0]
	s_nop 0
	v_pk_mul_f32 v[206:207], v[206:207], v[240:241]
	v_pk_fma_f32 v[204:205], v[104:105], v[136:137], v[0:1] op_sel_hi:[1,1,0]
	v_cvt_pk_bf16_f32 v162, v206, v207
	v_lshlrev_b32_e32 v206, 16, v163
	v_and_b32_e32 v207, 0xffff0000, v163
	v_pk_mul_f32 v[204:205], v[204:205], v[206:207]
	v_pk_fma_f32 v[222:223], v[98:99], v[130:131], v[0:1] op_sel_hi:[1,1,0]
	v_cvt_pk_bf16_f32 v163, v204, v205
	v_lshlrev_b32_e32 v204, 16, v164
	v_and_b32_e32 v205, 0xffff0000, v164
	v_pk_mul_f32 v[204:205], v[222:223], v[204:205]
	v_pk_fma_f32 v[220:221], v[100:101], v[132:133], v[0:1] op_sel_hi:[1,1,0]
	v_cvt_pk_bf16_f32 v164, v204, v205
	v_lshlrev_b32_e32 v204, 16, v165
	v_and_b32_e32 v205, 0xffff0000, v165
	v_pk_mul_f32 v[204:205], v[220:221], v[204:205]
	v_lshlrev_b32_e32 v206, 16, v158
	v_cvt_pk_bf16_f32 v165, v204, v205
	global_store_dwordx4 v[202:203], v[162:165], off
	v_mov_b32_e32 v0, v172
	v_and_b32_e32 v207, 0xffff0000, v158
	v_pk_fma_f32 v[164:165], v[86:87], v[134:135], v[0:1] op_sel_hi:[1,1,0]
	s_nop 0
	v_pk_mul_f32 v[164:165], v[164:165], v[206:207]
	v_pk_fma_f32 v[162:163], v[88:89], v[136:137], v[0:1] op_sel_hi:[1,1,0]
	v_cvt_pk_bf16_f32 v158, v164, v165
	v_lshlrev_b32_e32 v164, 16, v159
	v_and_b32_e32 v165, 0xffff0000, v159
	v_pk_mul_f32 v[162:163], v[162:163], v[164:165]
	v_pk_fma_f32 v[204:205], v[82:83], v[130:131], v[0:1] op_sel_hi:[1,1,0]
	v_cvt_pk_bf16_f32 v159, v162, v163
	v_lshlrev_b32_e32 v162, 16, v160
	v_and_b32_e32 v163, 0xffff0000, v160
	v_pk_mul_f32 v[162:163], v[204:205], v[162:163]
	v_pk_fma_f32 v[202:203], v[84:85], v[132:133], v[0:1] op_sel_hi:[1,1,0]
	v_cvt_pk_bf16_f32 v160, v162, v163
	v_lshlrev_b32_e32 v162, 16, v161
	v_and_b32_e32 v163, 0xffff0000, v161
	v_pk_mul_f32 v[162:163], v[202:203], v[162:163]
	s_nop 0
	v_cvt_pk_bf16_f32 v161, v162, v163
	v_lshl_add_u64 v[162:163], v[218:219], 0, v[200:201]
	global_store_dwordx4 v[162:163], v[158:161], off
	v_mov_b32_e32 v0, v173
	v_lshlrev_b32_e32 v200, 16, v154
	v_and_b32_e32 v201, 0xffff0000, v154
	v_pk_fma_f32 v[160:161], v[70:71], v[134:135], v[0:1] op_sel_hi:[1,1,0]
	s_nop 0
	v_pk_mul_f32 v[160:161], v[160:161], v[200:201]
	v_pk_fma_f32 v[158:159], v[72:73], v[136:137], v[0:1] op_sel_hi:[1,1,0]
	v_cvt_pk_bf16_f32 v154, v160, v161
	v_lshlrev_b32_e32 v160, 16, v155
	v_and_b32_e32 v161, 0xffff0000, v155
	v_pk_mul_f32 v[158:159], v[158:159], v[160:161]
	v_pk_fma_f32 v[164:165], v[66:67], v[130:131], v[0:1] op_sel_hi:[1,1,0]
	v_cvt_pk_bf16_f32 v155, v158, v159
	v_lshlrev_b32_e32 v158, 16, v156
	v_and_b32_e32 v159, 0xffff0000, v156
	v_pk_mul_f32 v[158:159], v[164:165], v[158:159]
	v_pk_fma_f32 v[162:163], v[68:69], v[132:133], v[0:1] op_sel_hi:[1,1,0]
	v_cvt_pk_bf16_f32 v156, v158, v159
	v_lshlrev_b32_e32 v158, 16, v157
	v_and_b32_e32 v159, 0xffff0000, v157
	v_pk_mul_f32 v[158:159], v[162:163], v[158:159]
	v_lshlrev_b32_e32 v162, 16, v150
	v_cvt_pk_bf16_f32 v157, v158, v159
	v_lshl_add_u64 v[158:159], v[218:219], 0, v[198:199]
	global_store_dwordx4 v[158:159], v[154:157], off
	v_mov_b32_e32 v0, v170
	v_and_b32_e32 v163, 0xffff0000, v150
	v_pk_fma_f32 v[156:157], v[54:55], v[134:135], v[0:1] op_sel_hi:[1,1,0]
	s_nop 0
	v_pk_mul_f32 v[156:157], v[156:157], v[162:163]
	v_pk_fma_f32 v[154:155], v[56:57], v[136:137], v[0:1] op_sel_hi:[1,1,0]
	v_cvt_pk_bf16_f32 v150, v156, v157
	v_lshlrev_b32_e32 v156, 16, v151
	v_and_b32_e32 v157, 0xffff0000, v151
	v_pk_mul_f32 v[154:155], v[154:155], v[156:157]
	v_pk_fma_f32 v[160:161], v[50:51], v[130:131], v[0:1] op_sel_hi:[1,1,0]
	v_cvt_pk_bf16_f32 v151, v154, v155
	v_lshlrev_b32_e32 v154, 16, v152
	v_and_b32_e32 v155, 0xffff0000, v152
	v_pk_mul_f32 v[154:155], v[160:161], v[154:155]
	v_pk_fma_f32 v[158:159], v[52:53], v[132:133], v[0:1] op_sel_hi:[1,1,0]
	v_cvt_pk_bf16_f32 v152, v154, v155
	v_lshlrev_b32_e32 v154, 16, v153
	v_and_b32_e32 v155, 0xffff0000, v153
	v_pk_mul_f32 v[154:155], v[158:159], v[154:155]
	v_lshlrev_b32_e32 v158, 16, v146
	v_cvt_pk_bf16_f32 v153, v154, v155
	v_lshl_add_u64 v[154:155], v[218:219], 0, v[194:195]
	global_store_dwordx4 v[154:155], v[150:153], off
	v_mov_b32_e32 v0, v171
	v_and_b32_e32 v159, 0xffff0000, v146
	v_pk_fma_f32 v[152:153], v[38:39], v[134:135], v[0:1] op_sel_hi:[1,1,0]
	s_nop 0
	v_pk_mul_f32 v[152:153], v[152:153], v[158:159]
	v_pk_fma_f32 v[150:151], v[40:41], v[136:137], v[0:1] op_sel_hi:[1,1,0]
	v_cvt_pk_bf16_f32 v146, v152, v153
	v_lshlrev_b32_e32 v152, 16, v147
	v_and_b32_e32 v153, 0xffff0000, v147
	v_pk_mul_f32 v[150:151], v[150:151], v[152:153]
	v_pk_fma_f32 v[156:157], v[34:35], v[130:131], v[0:1] op_sel_hi:[1,1,0]
	v_cvt_pk_bf16_f32 v147, v150, v151
	v_lshlrev_b32_e32 v150, 16, v148
	v_and_b32_e32 v151, 0xffff0000, v148
	v_pk_mul_f32 v[150:151], v[156:157], v[150:151]
	v_pk_fma_f32 v[154:155], v[36:37], v[132:133], v[0:1] op_sel_hi:[1,1,0]
	v_cvt_pk_bf16_f32 v148, v150, v151
	v_lshlrev_b32_e32 v150, 16, v149
	v_and_b32_e32 v151, 0xffff0000, v149
	v_pk_mul_f32 v[150:151], v[154:155], v[150:151]
	v_lshlrev_b32_e32 v154, 16, v142
	v_cvt_pk_bf16_f32 v149, v150, v151
	v_lshl_add_u64 v[150:151], v[218:219], 0, v[192:193]
	global_store_dwordx4 v[150:151], v[146:149], off
	v_mov_b32_e32 v0, v172
	v_and_b32_e32 v155, 0xffff0000, v142
	v_pk_fma_f32 v[148:149], v[22:23], v[134:135], v[0:1] op_sel_hi:[1,1,0]
	s_nop 0
	v_pk_mul_f32 v[148:149], v[148:149], v[154:155]
	v_pk_fma_f32 v[146:147], v[24:25], v[136:137], v[0:1] op_sel_hi:[1,1,0]
	v_cvt_pk_bf16_f32 v142, v148, v149
	v_lshlrev_b32_e32 v148, 16, v143
	v_and_b32_e32 v149, 0xffff0000, v143
	v_pk_mul_f32 v[146:147], v[146:147], v[148:149]
	v_pk_fma_f32 v[152:153], v[18:19], v[130:131], v[0:1] op_sel_hi:[1,1,0]
	v_cvt_pk_bf16_f32 v143, v146, v147
	v_lshlrev_b32_e32 v146, 16, v144
	v_and_b32_e32 v147, 0xffff0000, v144
	v_pk_mul_f32 v[146:147], v[152:153], v[146:147]
	v_pk_fma_f32 v[150:151], v[20:21], v[132:133], v[0:1] op_sel_hi:[1,1,0]
	v_cvt_pk_bf16_f32 v144, v146, v147
	v_lshlrev_b32_e32 v146, 16, v145
	v_and_b32_e32 v147, 0xffff0000, v145
	v_pk_mul_f32 v[146:147], v[150:151], v[146:147]
	s_nop 0
	v_cvt_pk_bf16_f32 v145, v146, v147
	v_lshl_add_u64 v[146:147], v[218:219], 0, v[190:191]
	global_store_dwordx4 v[146:147], v[142:145], off
	v_mov_b32_e32 v0, v173
	v_pk_fma_f32 v[134:135], v[6:7], v[134:135], v[0:1] op_sel_hi:[1,1,0]
	v_pk_fma_f32 v[142:143], v[4:5], v[132:133], v[0:1] op_sel_hi:[1,1,0]
	v_pk_fma_f32 v[132:133], v[2:3], v[130:131], v[0:1] op_sel_hi:[1,1,0]
	v_lshlrev_b32_e32 v130, 16, v138
	v_and_b32_e32 v131, 0xffff0000, v138
	v_pk_fma_f32 v[136:137], v[8:9], v[136:137], v[0:1] op_sel_hi:[1,1,0]
	v_pk_mul_f32 v[130:131], v[134:135], v[130:131]
	v_lshlrev_b32_e32 v134, 16, v139
	v_and_b32_e32 v135, 0xffff0000, v139
	v_pk_mul_f32 v[134:135], v[136:137], v[134:135]
	v_cvt_pk_bf16_f32 v130, v130, v131
	v_cvt_pk_bf16_f32 v131, v134, v135
	v_lshlrev_b32_e32 v134, 16, v140
	v_and_b32_e32 v135, 0xffff0000, v140
	v_pk_mul_f32 v[132:133], v[132:133], v[134:135]
	v_lshlrev_b32_e32 v134, 16, v141
	v_and_b32_e32 v135, 0xffff0000, v141
	v_pk_mul_f32 v[134:135], v[142:143], v[134:135]
	v_cvt_pk_bf16_f32 v132, v132, v133
	v_cvt_pk_bf16_f32 v133, v134, v135
	v_lshl_add_u64 v[134:135], v[218:219], 0, v[188:189]
	global_store_dwordx4 v[134:135], v[130:133], off
